# P5 scan/attention order split by workgroup bit 5 (the 4 workgroups that share one head's K/V keep the same order)
# speedup vs baseline: 1.0001x; 1.0001x over previous
.LBB0_670:
	v_writelane_b32 v255, s64, 53
	s_cmpk_gt_i32 s16, 0xff
	v_mbcnt_lo_u32_b32 v0, -1, 0
	v_mbcnt_hi_u32_b32 v0, -1, v0
	s_cbranch_scc1 .LBB0_711
	s_bitcmp1_b32 s64, 5
	s_cbranch_scc0 .Lp5_attn_entry
	s_cmp_eq_u32 s98, 0x52
	s_cbranch_scc1 .Lp5_attn_entry
	s_mov_b32 s98, 0x51
	s_mov_b32 s99, s16
	v_readlane_b32 s73, v254, 20
	s_branch .LBB0_711
